# hyena short-conv weight loads of x1/x2 streams issued together with the v stream loads (L1 w2, L3 w2+w3)
# baseline (speedup 1.0000x reference)
.LBB0_1490:
	s_or_b64 exec, exec, s[0:1]
	v_readlane_b32 s48, v250, 41
	s_lshl_b64 s[0:1], s[20:21], 2
	v_readlane_b32 s58, v250, 51
	v_readlane_b32 s59, v250, 52
	s_add_u32 s30, s58, s0
	v_readlane_b32 s60, v250, 53
	s_addc_u32 s31, s59, s1
	v_readlane_b32 s61, v250, 54
	s_add_u32 s34, s60, s0
	s_addc_u32 s35, s61, s1
	global_load_dword v140, v115, s[30:31]
	global_load_dword v119, v130, s[30:31]
	global_load_dword v141, v115, s[34:35]
	global_load_dword v118, v131, s[30:31]
	global_load_dword v121, v133, s[30:31]
	global_load_dword v120, v134, s[30:31]
	global_load_dword v143, v132, s[30:31]
	global_load_dword v142, v132, s[34:35]
	v_ashrrev_i32_e32 v22, 31, v139
	v_add_u32_sdwa v129, v139, v22 dst_sel:DWORD dst_unused:UNUSED_PAD src0_sel:DWORD src1_sel:BYTE_3
	v_readlane_b32 s49, v250, 42
	v_readlane_b32 s50, v250, 43
	v_readlane_b32 s51, v250, 44
	v_readlane_b32 s52, v250, 45
	v_readlane_b32 s53, v250, 46
	v_readlane_b32 s54, v250, 47
	v_readlane_b32 s55, v250, 48
	v_readlane_b32 s56, v250, 49
	v_readlane_b32 s57, v250, 50
	v_readlane_b32 s62, v250, 55
	v_readlane_b32 s63, v250, 56
	s_and_saveexec_b64 s[0:1], vcc
	s_cbranch_execz .LBB0_1492
	v_lshlrev_b32_e32 v22, 16, v67
	s_waitcnt vmcnt(1)
	v_fma_f32 v41, v140, v22, v141
	v_and_b32_e32 v22, 0xffff0000, v36
	v_lshlrev_b32_e32 v25, 16, v36
	v_mov_b32_e32 v24, v22
	s_waitcnt vmcnt(0)
	v_pk_mul_f32 v[30:31], v[118:119], v[24:25]
	v_and_b32_e32 v23, 16, v36
	v_add_f32_e32 v24, v31, v41
	v_add_f32_e32 v36, v30, v24
	v_and_b32_e32 v24, 0xffff0000, v37
	v_lshlrev_b32_e32 v31, 16, v37
	v_mov_b32_e32 v30, v24
	v_fma_f32 v42, v140, v22, v141
	v_pk_mov_b32 v[22:23], v[30:31], v[22:23] op_sel:[1,0]
	v_fma_f32 v41, v140, v25, v141
	v_pk_mul_f32 v[22:23], v[118:119], v[22:23]
	v_and_b32_e32 v25, 16, v37
	v_add_f32_e32 v23, v23, v41
	v_add_f32_e32 v37, v22, v23
	v_pk_mul_f32 v[22:23], v[118:119], v[30:31]
	v_fma_f32 v43, v140, v24, v141
	v_add_f32_e32 v23, v23, v42
	v_add_f32_e32 v41, v22, v23
	v_and_b32_e32 v22, 0xffff0000, v38
	v_fma_f32 v42, v140, v31, v141
	v_lshlrev_b32_e32 v31, 16, v38
	v_mov_b32_e32 v30, v22
	v_pk_mov_b32 v[24:25], v[30:31], v[24:25] op_sel:[1,0]
	v_and_b32_e32 v23, 16, v38
	v_pk_mul_f32 v[24:25], v[118:119], v[24:25]
	v_lshrrev_b32_e32 v40, 8, v129
	v_add_f32_e32 v25, v25, v42
	v_add_f32_e32 v38, v24, v25
	v_pk_mul_f32 v[24:25], v[118:119], v[30:31]
	v_fma_f32 v42, v140, v22, v141
	v_add_f32_e32 v25, v25, v43
	v_add_f32_e32 v30, v24, v25
	v_and_b32_e32 v24, 0xffff0000, v39
	v_lshlrev_b32_e32 v25, 16, v39
	v_pk_mov_b32 v[22:23], v[24:25], v[22:23] op_sel:[1,0]
	v_fma_f32 v31, v140, v31, v141
	v_pk_mul_f32 v[22:23], v[118:119], v[22:23]
	v_mov_b32_e32 v69, v24
	v_add_f32_e32 v23, v23, v31
	v_add_f32_e32 v31, v22, v23
	v_pk_mul_f32 v[22:23], v[118:119], v[24:25]
	v_fma_f32 v25, v140, v25, v141
	v_add_f32_e32 v23, v23, v42
	v_add_f32_e32 v39, v22, v23
	s_waitcnt vmcnt(0)
	v_lshlrev_b32_e32 v68, 16, v68
	v_pk_mul_f32 v[22:23], v[68:69], v[118:119]
	s_nop 0
	v_add_f32_e32 v23, v23, v25
	v_add_f32_e32 v25, v22, v23
	v_cvt_pk_bf16_f32 v22, v36, v37
	v_cvt_pk_bf16_f32 v23, v41, v38
	v_cvt_pk_bf16_f32 v24, v30, v31
	v_mad_i32_i24 v30, v40, s70, v123
	v_lshl_add_u32 v30, v30, 1, 0
	v_cvt_pk_bf16_f32 v25, v39, v25
	ds_write_b128 v30, v[22:25] offset:33920

.LBB0_1498:
	s_or_b64 exec, exec, s[0:1]
	s_waitcnt vmcnt(0)
	s_and_saveexec_b64 s[0:1], vcc
	s_cbranch_execz .LBB0_1504
	s_waitcnt vmcnt(8)
	v_lshlrev_b32_e32 v18, 16, v59
	s_waitcnt vmcnt(0)
	v_fma_f32 v25, v143, v18, v142
	v_and_b32_e32 v18, 0xffff0000, v14
	v_lshlrev_b32_e32 v21, 16, v14
	v_mov_b32_e32 v20, v18
	v_pk_mul_f32 v[22:23], v[120:121], v[20:21]
	v_and_b32_e32 v19, 16, v14
	v_add_f32_e32 v14, v23, v25
	v_and_b32_e32 v20, 0xffff0000, v15
	v_add_f32_e32 v22, v22, v14
	v_fma_f32 v23, v143, v21, v142
	v_and_b32_e32 v21, 16, v15
	v_lshlrev_b32_e32 v15, 16, v15
	v_mov_b32_e32 v14, v20
	v_fma_f32 v25, v143, v18, v142
	v_pk_mov_b32 v[18:19], v[14:15], v[18:19] op_sel:[1,0]
	v_fma_f32 v27, v143, v20, v142
	v_pk_mul_f32 v[18:19], v[120:121], v[18:19]
	v_fma_f32 v26, v143, v15, v142
	v_add_f32_e32 v19, v19, v23
	v_add_f32_e32 v23, v18, v19
	v_pk_mul_f32 v[18:19], v[120:121], v[14:15]
	v_and_b32_e32 v15, 16, v16
	v_add_f32_e32 v14, v19, v25
	v_add_f32_e32 v25, v18, v14
	v_and_b32_e32 v14, 0xffff0000, v16
	v_lshlrev_b32_e32 v19, 16, v16
	v_mov_b32_e32 v18, v14
	v_pk_mov_b32 v[20:21], v[18:19], v[20:21] op_sel:[1,0]
	v_lshrrev_b32_e32 v24, 8, v129
	v_pk_mul_f32 v[20:21], v[120:121], v[20:21]
	s_nop 0
	v_add_f32_e32 v16, v21, v26
	v_add_f32_e32 v26, v20, v16
	v_pk_mul_f32 v[20:21], v[120:121], v[18:19]
	v_fma_f32 v19, v143, v19, v142
	v_add_f32_e32 v16, v21, v27
	v_add_f32_e32 v18, v20, v16
	v_and_b32_e32 v16, 0xffff0000, v17
	v_lshlrev_b32_e32 v17, 16, v17
	v_fma_f32 v20, v143, v14, v142
	v_pk_mov_b32 v[14:15], v[16:17], v[14:15] op_sel:[1,0]
	v_mov_b32_e32 v61, v16
	v_pk_mul_f32 v[14:15], v[120:121], v[14:15]
	s_nop 0
	v_add_f32_e32 v15, v15, v19
	v_add_f32_e32 v19, v14, v15
	v_pk_mul_f32 v[14:15], v[120:121], v[16:17]
	v_fma_f32 v17, v143, v17, v142
	v_add_f32_e32 v15, v15, v20
	v_add_f32_e32 v20, v14, v15
	s_waitcnt vmcnt(0)
	v_lshlrev_b32_e32 v60, 16, v60
	v_pk_mul_f32 v[14:15], v[60:61], v[120:121]
	s_nop 0
	v_add_f32_e32 v15, v15, v17
	v_add_f32_e32 v17, v14, v15
	v_cvt_pk_bf16_f32 v14, v22, v23
	v_cvt_pk_bf16_f32 v15, v25, v26
	v_cvt_pk_bf16_f32 v16, v18, v19
	v_mad_i32_i24 v18, v24, s71, v123
	v_lshl_add_u32 v18, v18, 1, 0
	v_add_u32_e32 v18, 0x14100, v18
	v_cvt_pk_bf16_f32 v17, v20, v17
	ds_write_b128 v18, v[14:17]
	s_or_b64 exec, exec, s[0:1]
	s_and_saveexec_b64 s[0:1], s[14:15]
	s_cbranch_execnz .LBB0_1505

.LBB0_3387:
	s_or_b64 exec, exec, s[0:1]
	s_lshl_b64 s[0:1], s[18:19], 2
	s_add_u32 s22, s31, s0
	s_addc_u32 s23, s34, s1
	s_add_u32 s24, s35, s0
	s_addc_u32 s25, s36, s1
	global_load_dword v24, v115, s[22:23]
	global_load_dword v23, v126, s[22:23]
	global_load_dword v25, v115, s[24:25]
	global_load_dword v22, v127, s[22:23]
	global_load_dword v240, v129, s[22:23]
	global_load_dword v241, v130, s[22:23]
	global_load_dword v242, v128, s[22:23]
	global_load_dword v243, v128, s[24:25]
	global_load_dword v244, v132, s[22:23]
	global_load_dword v245, v133, s[22:23]
	global_load_dword v246, v131, s[22:23]
	global_load_dword v247, v131, s[24:25]
	v_ashrrev_i32_e32 v26, 31, v135
	v_add_u32_sdwa v125, v135, v26 dst_sel:DWORD dst_unused:UNUSED_PAD src0_sel:DWORD src1_sel:BYTE_3
	s_and_saveexec_b64 s[0:1], vcc
	s_cbranch_execz .LBB0_3389
	s_waitcnt vmcnt(4)
	v_lshlrev_b32_e32 v26, 16, v67
	s_waitcnt vmcnt(1)
	v_fma_f32 v41, v24, v26, v25
	v_and_b32_e32 v26, 0xffff0000, v42
	v_lshlrev_b32_e32 v37, 16, v42
	v_mov_b32_e32 v36, v26
	s_waitcnt vmcnt(0)
	v_pk_mul_f32 v[38:39], v[22:23], v[36:37]
	v_and_b32_e32 v27, 16, v42
	v_add_f32_e32 v36, v39, v41
	v_add_f32_e32 v41, v38, v36
	v_and_b32_e32 v36, 0xffff0000, v43
	v_lshlrev_b32_e32 v39, 16, v43
	v_mov_b32_e32 v38, v36
	v_fma_f32 v67, v24, v26, v25
	v_pk_mov_b32 v[26:27], v[38:39], v[26:27] op_sel:[1,0]
	v_fma_f32 v42, v24, v37, v25
	v_pk_mul_f32 v[26:27], v[22:23], v[26:27]
	v_and_b32_e32 v37, 16, v43
	v_add_f32_e32 v27, v27, v42
	v_add_f32_e32 v42, v26, v27
	v_pk_mul_f32 v[26:27], v[22:23], v[38:39]
	v_fma_f32 v69, v24, v36, v25
	v_add_f32_e32 v27, v27, v67
	v_add_f32_e32 v43, v26, v27
	v_and_b32_e32 v26, 0xffff0000, v44
	v_fma_f32 v67, v24, v39, v25
	v_lshlrev_b32_e32 v39, 16, v44
	v_mov_b32_e32 v38, v26
	v_pk_mov_b32 v[36:37], v[38:39], v[36:37] op_sel:[1,0]
	v_and_b32_e32 v27, 16, v44
	v_pk_mul_f32 v[36:37], v[22:23], v[36:37]
	v_lshrrev_b32_e32 v40, 8, v125
	v_add_f32_e32 v37, v37, v67
	v_add_f32_e32 v44, v36, v37
	v_pk_mul_f32 v[36:37], v[22:23], v[38:39]
	v_fma_f32 v67, v24, v26, v25
	v_add_f32_e32 v37, v37, v69
	v_add_f32_e32 v38, v36, v37
	v_and_b32_e32 v36, 0xffff0000, v45
	v_lshlrev_b32_e32 v37, 16, v45
	v_pk_mov_b32 v[26:27], v[36:37], v[26:27] op_sel:[1,0]
	v_fma_f32 v39, v24, v39, v25
	v_pk_mul_f32 v[26:27], v[22:23], v[26:27]
	v_mov_b32_e32 v69, v36
	v_add_f32_e32 v27, v27, v39
	v_add_f32_e32 v39, v26, v27
	v_pk_mul_f32 v[26:27], v[22:23], v[36:37]
	v_fma_f32 v37, v24, v37, v25
	v_add_f32_e32 v27, v27, v67
	v_add_f32_e32 v45, v26, v27
	s_waitcnt vmcnt(0)
	v_lshlrev_b32_e32 v68, 16, v68
	v_pk_mul_f32 v[26:27], v[68:69], v[22:23]
	v_cvt_pk_bf16_f32 v36, v41, v42
	s_nop 0
	v_add_f32_e32 v27, v27, v37
	v_add_f32_e32 v26, v26, v27
	v_cvt_pk_bf16_f32 v37, v43, v44
	v_cvt_pk_bf16_f32 v38, v38, v39
	v_cvt_pk_bf16_f32 v39, v45, v26
	v_mad_i32_i24 v26, v40, s55, v119
	v_lshl_add_u32 v26, v26, 1, 0
	ds_write_b128 v26, v[36:39] offset:33920

.LBB0_3395:
	s_or_b64 exec, exec, s[0:1]
	s_waitcnt vmcnt(0)
	v_mov_b32_e32 v19, v240
	v_mov_b32_e32 v18, v241
	v_mov_b32_e32 v21, v242
	v_mov_b32_e32 v20, v243
	s_and_saveexec_b64 s[0:1], vcc
	s_cbranch_execz .LBB0_3401
	s_waitcnt vmcnt(4)
	v_lshlrev_b32_e32 v22, 16, v59
	s_waitcnt vmcnt(0)
	v_fma_f32 v29, v21, v22, v20
	v_and_b32_e32 v22, 0xffff0000, v14
	v_lshlrev_b32_e32 v25, 16, v14
	v_mov_b32_e32 v24, v22
	v_pk_mul_f32 v[26:27], v[18:19], v[24:25]
	v_and_b32_e32 v23, 16, v14
	v_add_f32_e32 v14, v27, v29
	v_and_b32_e32 v24, 0xffff0000, v15
	v_add_f32_e32 v26, v26, v14
	v_fma_f32 v27, v21, v25, v20
	v_and_b32_e32 v25, 16, v15
	v_lshlrev_b32_e32 v15, 16, v15
	v_mov_b32_e32 v14, v24
	v_fma_f32 v29, v21, v22, v20
	v_pk_mov_b32 v[22:23], v[14:15], v[22:23] op_sel:[1,0]
	v_fma_f32 v31, v21, v24, v20
	v_pk_mul_f32 v[22:23], v[18:19], v[22:23]
	v_fma_f32 v30, v21, v15, v20
	v_add_f32_e32 v23, v23, v27
	v_add_f32_e32 v27, v22, v23
	v_pk_mul_f32 v[22:23], v[18:19], v[14:15]
	v_and_b32_e32 v15, 16, v16
	v_add_f32_e32 v14, v23, v29
	v_add_f32_e32 v29, v22, v14
	v_and_b32_e32 v14, 0xffff0000, v16
	v_lshlrev_b32_e32 v23, 16, v16
	v_mov_b32_e32 v22, v14
	v_pk_mov_b32 v[24:25], v[22:23], v[24:25] op_sel:[1,0]
	v_lshrrev_b32_e32 v28, 8, v125
	v_pk_mul_f32 v[24:25], v[18:19], v[24:25]
	s_nop 0
	v_add_f32_e32 v16, v25, v30
	v_add_f32_e32 v30, v24, v16
	v_pk_mul_f32 v[24:25], v[18:19], v[22:23]
	v_fma_f32 v23, v21, v23, v20
	v_add_f32_e32 v16, v25, v31
	v_add_f32_e32 v22, v24, v16
	v_and_b32_e32 v16, 0xffff0000, v17
	v_lshlrev_b32_e32 v17, 16, v17
	v_fma_f32 v24, v21, v14, v20
	v_pk_mov_b32 v[14:15], v[16:17], v[14:15] op_sel:[1,0]
	v_mov_b32_e32 v61, v16
	v_pk_mul_f32 v[14:15], v[18:19], v[14:15]
	s_nop 0
	v_add_f32_e32 v15, v15, v23
	v_add_f32_e32 v23, v14, v15
	v_pk_mul_f32 v[14:15], v[18:19], v[16:17]
	v_fma_f32 v17, v21, v17, v20
	v_add_f32_e32 v15, v15, v24
	v_add_f32_e32 v24, v14, v15
	s_waitcnt vmcnt(0)
	v_lshlrev_b32_e32 v60, 16, v60
	v_pk_mul_f32 v[14:15], v[60:61], v[18:19]
	s_nop 0
	v_add_f32_e32 v15, v15, v17
	v_add_f32_e32 v17, v14, v15
	v_cvt_pk_bf16_f32 v14, v26, v27
	v_cvt_pk_bf16_f32 v15, v29, v30
	v_cvt_pk_bf16_f32 v16, v22, v23
	v_mad_i32_i24 v22, v28, s58, v119
	v_lshl_add_u32 v22, v22, 1, 0
	v_add_u32_e32 v22, 0x14100, v22
	v_cvt_pk_bf16_f32 v17, v24, v17
	ds_write_b128 v22, v[14:17]
	s_or_b64 exec, exec, s[0:1]
	s_and_saveexec_b64 s[0:1], s[14:15]
	s_cbranch_execnz .LBB0_3402

.LBB0_3461:
	s_or_b64 exec, exec, s[0:1]
	s_waitcnt lgkmcnt(0)
	s_barrier
	s_waitcnt vmcnt(0)
	v_mov_b32_e32 v3, v244
	v_mov_b32_e32 v2, v245
	v_mov_b32_e32 v5, v246
	v_mov_b32_e32 v4, v247
	s_and_saveexec_b64 s[0:1], vcc
	s_cbranch_execz .LBB0_3467
	s_waitcnt vmcnt(4)
	v_lshlrev_b32_e32 v6, 16, v157
	s_waitcnt vmcnt(0)
	v_fma_f32 v13, v5, v6, v4
	v_and_b32_e32 v6, 0xffff0000, v90
	v_lshlrev_b32_e32 v9, 16, v90
	v_mov_b32_e32 v8, v6
	v_pk_mul_f32 v[10:11], v[2:3], v[8:9]
	v_and_b32_e32 v7, 16, v90
	v_add_f32_e32 v8, v11, v13
	v_add_f32_e32 v13, v10, v8
	v_and_b32_e32 v8, 0xffff0000, v91
	v_lshlrev_b32_e32 v11, 16, v91
	v_mov_b32_e32 v10, v8
	v_fma_f32 v15, v5, v6, v4
	v_pk_mov_b32 v[6:7], v[10:11], v[6:7] op_sel:[1,0]
	v_fma_f32 v14, v5, v9, v4
	v_pk_mul_f32 v[6:7], v[2:3], v[6:7]
	v_and_b32_e32 v9, 16, v91
	v_add_f32_e32 v7, v7, v14
	v_add_f32_e32 v14, v6, v7
	v_pk_mul_f32 v[6:7], v[2:3], v[10:11]
	v_fma_f32 v16, v5, v11, v4
	v_add_f32_e32 v7, v7, v15
	v_add_f32_e32 v15, v6, v7
	v_and_b32_e32 v6, 0xffff0000, v92
	v_lshlrev_b32_e32 v11, 16, v92
	v_mov_b32_e32 v10, v6
	v_fma_f32 v17, v5, v8, v4
	v_pk_mov_b32 v[8:9], v[10:11], v[8:9] op_sel:[1,0]
	v_and_b32_e32 v7, 16, v92
	v_pk_mul_f32 v[8:9], v[2:3], v[8:9]
	v_lshrrev_b32_e32 v12, 8, v125
	v_add_f32_e32 v9, v9, v16
	v_add_f32_e32 v16, v8, v9
	v_pk_mul_f32 v[8:9], v[2:3], v[10:11]
	v_fma_f32 v11, v5, v11, v4
	v_add_f32_e32 v9, v9, v17
	v_add_f32_e32 v10, v8, v9
	v_and_b32_e32 v8, 0xffff0000, v93
	v_lshlrev_b32_e32 v9, 16, v93
	v_fma_f32 v17, v5, v6, v4
	v_pk_mov_b32 v[6:7], v[8:9], v[6:7] op_sel:[1,0]
	v_mov_b32_e32 v125, v8
	v_pk_mul_f32 v[6:7], v[2:3], v[6:7]
	s_nop 0
	v_add_f32_e32 v7, v7, v11
	v_add_f32_e32 v11, v6, v7
	v_pk_mul_f32 v[6:7], v[2:3], v[8:9]
	v_fma_f32 v9, v5, v9, v4
	v_add_f32_e32 v7, v7, v17
	v_add_f32_e32 v17, v6, v7
	s_waitcnt vmcnt(0)
	v_lshlrev_b32_e32 v124, 16, v124
	v_pk_mul_f32 v[6:7], v[124:125], v[2:3]
	s_nop 0
	v_add_f32_e32 v7, v7, v9
	v_add_f32_e32 v9, v6, v7
	v_cvt_pk_bf16_f32 v6, v13, v14
	v_cvt_pk_bf16_f32 v7, v15, v16
	v_cvt_pk_bf16_f32 v8, v10, v11
	v_mad_i32_i24 v10, v12, s58, v119
	v_lshl_add_u32 v10, v10, 1, 0
	v_add_u32_e32 v10, 0x14100, v10
	v_cvt_pk_bf16_f32 v9, v17, v9
	ds_write_b128 v10, v[6:9]
	s_or_b64 exec, exec, s[0:1]
	s_and_saveexec_b64 s[0:1], s[14:15]
	s_cbranch_execnz .LBB0_3468
